# FFN1-down epilogue: gain reloads issued ahead of the two stores into a spare register quad, waited with vmcnt(2)
# speedup vs baseline: 1.0038x; 1.0027x over previous
; #define ER_LOAD(q, buf) do { _Pragma("unroll") for (int mm = 0; mm < 2; ++mm) { const size_t off_ = (size_t)(row0 + ((q) >> 1) * HALF + (2 * ((q) & 1) + mm) * 16) * ldc + col0; \
;             _Pragma("unroll") for (int bj = 0; bj < 2; ++bj) _Pragma("unroll") for (int n = 0; n < 2; ++n) pre[buf][mm][bj][n] = *(const f32x4*)(base + off_ + bj * HALF + n * 16); } } while (0)
;     __device__ __forceinline__ void operator()(const f32x4 (&acc)[2][2][4][2], const Unit& u, int wr, int wc, int fr, int fq) const {
;         const int row0 = u.pm * BM + wr * 64 + fr, col0 = u.pn * BM + wc * 32 + 4 * fq;
;         bf16_t* XB = (bf16_t*)(ws + XBOFF); float* stat = (float*)(ws + STOFF); const float* gain = (const float*)(ws + GOFF);
;         typedef unsigned u32x2_ __attribute__((ext_vector_type(2)));
;         f32x4 pre[2][2][2][2]; float ssq[8];
;     ...
;         ER_LOAD(0, 0);
; #pragma unroll
;         for (int q = 0; q < 4; ++q) {
;             if (q == 0) ER_LOAD(1, 1); else if (q == 1) ER_LOAD(2, 0); else if (q == 2) ER_LOAD(3, 1);
; #pragma unroll
;             for (int mm = 0; mm < 2; ++mm) { const int ai = q >> 1, m = 2 * (q & 1) + mm; const size_t off = (size_t)(row0 + ai * HALF + m * 16) * ldc + col0; float ss = 0.f;
;                 const int rl = wr * 64 + fr + ai * HALF + m * 16, cl0 = col0; const size_t xoff = (size_t)u.pm * ((size_t)ldc * BM) + (size_t)rl * 64;
; #pragma unroll
;                 for (int bj = 0; bj < 2; ++bj)
; #pragma unroll
;                     for (int n = 0; n < 2; ++n) {
;                         const f32x4 o = pre[q & 1][mm][bj][n] + acc[ai][bj][m][n] * scale;
;                         *(f32x4*)(out + off + bj * HALF + n * 16) = o;
;                         if (COPY) { const f32x4 gn = *(const f32x4*)(gain + col0 + bj * HALF + n * 16); u32x2_ w; w.x = pk_bf16(o[0] * gn[0], o[1] * gn[1]); w.y = pk_bf16(o[2] * gn[2], o[3] * gn[3]); *(u32x2_*)(XB + xoff + (size_t)((cl0 + bj * HALF + n * 16) >> 6) * (256 * 64) + ((cl0 + bj * HALF + n * 16) & 63)) = w; ss += (o[0] * o[0] + o[1] * o[1]) + (o[2] * o[2] + o[3] * o[3]); } }
;                 if (COPY) { ss += __shfl_xor(ss, 16); ss += __shfl_xor(ss, 32); ssq[2 * q + mm] = ss; } }
;         }
.LBB0_277:
	s_lshl_b32 s3, s3, 8
	s_or_b32 s3, s3, s77
	v_or_b32_e32 v130, s3, v239
	v_lshl_add_u32 v222, s34, 8, v196
	v_ashrrev_i32_e32 v131, 31, v130
	v_lshlrev_b64 v[226:227], 2, v[130:131]
	v_ashrrev_i32_e32 v223, 31, v222
	v_lshl_add_u64 v[228:229], s[8:9], 0, v[226:227]
	v_lshlrev_b64 v[230:231], 14, v[222:223]
	v_lshl_add_u64 v[130:131], v[228:229], 0, v[230:231]
	global_load_dwordx4 v[158:161], v[130:131], off
	v_or_b32_e32 v132, 16, v222
	v_or_b32_e32 v134, 32, v222
	v_or_b32_e32 v136, 48, v222
	v_ashrrev_i32_e32 v133, 31, v132
	v_ashrrev_i32_e32 v135, 31, v134
	v_ashrrev_i32_e32 v137, 31, v136
	v_lshlrev_b64 v[152:153], 14, v[132:133]
	v_lshlrev_b64 v[150:151], 14, v[134:135]
	v_lshl_add_u64 v[132:133], s[48:49], 0, v[230:231]
	v_lshlrev_b64 v[232:233], 14, v[136:137]
	v_lshl_add_u64 v[248:249], v[132:133], 0, v[226:227]
	v_lshl_add_u64 v[132:133], v[228:229], 0, v[152:153]
	v_lshl_add_u64 v[134:135], v[228:229], 0, v[150:151]
	v_lshl_add_u64 v[224:225], s[18:19], 0, v[226:227]
	v_lshl_add_u64 v[250:251], v[228:229], 0, v[232:233]
	global_load_dwordx4 v[166:169], v[130:131], off offset:64
	global_load_dwordx4 v[174:177], v[130:131], off offset:512
	global_load_dwordx4 v[182:185], v[130:131], off offset:576
	global_load_dwordx4 v[186:189], v[132:133], off
	global_load_dwordx4 v[234:237], v[132:133], off offset:64
	global_load_dwordx4 v[244:247], v[132:133], off offset:512
	global_load_dwordx4 v[142:145], v[132:133], off offset:576
	global_load_dwordx4 v[138:141], v[134:135], off
	global_load_dwordx4 v[178:181], v[134:135], off offset:64
	global_load_dwordx4 v[170:173], v[134:135], off offset:512
	global_load_dwordx4 v[162:165], v[134:135], off offset:576
	global_load_dwordx4 v[154:157], v[250:251], off
	global_load_dwordx4 v[146:149], v[250:251], off offset:64
	s_nop 0
	global_load_dwordx4 v[134:137], v[250:251], off offset:512
	global_load_dwordx4 v[130:133], v[250:251], off offset:576
	s_ashr_i32 s35, s34, 31
	s_lshl_b64 s[34:35], s[34:35], 21
	s_add_u32 s34, s78, s34
	s_addc_u32 s35, s79, s35
	s_ashr_i32 s38, s3, 6
	s_ashr_i32 s39, s38, 31
	v_bitop3_b32 v194, s3, 44, v239 bitop3:0xc8
	v_lshl_add_u64 v[250:251], s[34:35], 0, v[198:199]
	s_lshl_b64 s[36:37], s[38:39], 15
	v_lshlrev_b32_e32 v194, 1, v194
	v_lshl_add_u64 v[252:253], v[250:251], 0, s[36:37]
	v_lshl_add_u64 v[252:253], v[252:253], 0, v[194:195]
	s_or_b32 s38, s38, 2
	s_ashr_i32 s39, s38, 31
	s_lshl_b64 s[38:39], s[38:39], 15
	v_lshl_add_u64 v[152:153], s[48:49], 0, v[152:153]
	v_lshl_add_u64 v[152:153], v[152:153], 0, v[226:227]
	v_lshl_add_u64 v[150:151], s[48:49], 0, v[150:151]
	s_waitcnt vmcnt(0)
	v_pk_fma_f32 v[92:93], v[92:93], 0.5, v[160:161] op_sel_hi:[1,0,1]
	v_pk_fma_f32 v[90:91], v[90:91], 0.5, v[158:159] op_sel_hi:[1,0,1]
	global_store_dwordx4 v[248:249], v[90:93], off
	global_load_dwordx4 v[158:161], v[224:225], off
	v_pk_fma_f32 v[100:101], v[100:101], 0.5, v[168:169] op_sel_hi:[1,0,1]
	v_pk_fma_f32 v[98:99], v[98:99], 0.5, v[166:167] op_sel_hi:[1,0,1]
	v_pk_fma_f32 v[108:109], v[108:109], 0.5, v[176:177] op_sel_hi:[1,0,1]
	v_pk_fma_f32 v[106:107], v[106:107], 0.5, v[174:175] op_sel_hi:[1,0,1]
	v_lshl_add_u64 v[166:167], v[250:251], 0, s[38:39]
	v_lshl_add_u64 v[166:167], v[166:167], 0, v[194:195]
	v_pk_fma_f32 v[116:117], v[116:117], 0.5, v[184:185] op_sel_hi:[1,0,1]
	v_pk_fma_f32 v[114:115], v[114:115], 0.5, v[182:183] op_sel_hi:[1,0,1]
	v_pk_fma_f32 v[124:125], v[124:125], 0.5, v[188:189] op_sel_hi:[1,0,1]
	v_pk_fma_f32 v[122:123], v[122:123], 0.5, v[186:187] op_sel_hi:[1,0,1]
	v_pk_fma_f32 v[128:129], v[128:129], 0.5, v[236:237] op_sel_hi:[1,0,1]
	v_pk_fma_f32 v[126:127], v[126:127], 0.5, v[234:235] op_sel_hi:[1,0,1]
	v_pk_fma_f32 v[120:121], v[120:121], 0.5, v[246:247] op_sel_hi:[1,0,1]
	v_pk_fma_f32 v[118:119], v[118:119], 0.5, v[244:245] op_sel_hi:[1,0,1]
	v_pk_fma_f32 v[112:113], v[112:113], 0.5, v[144:145] op_sel_hi:[1,0,1]
	v_pk_fma_f32 v[110:111], v[110:111], 0.5, v[142:143] op_sel_hi:[1,0,1]
	v_pk_fma_f32 v[104:105], v[104:105], 0.5, v[140:141] op_sel_hi:[1,0,1]
	v_pk_fma_f32 v[102:103], v[102:103], 0.5, v[138:139] op_sel_hi:[1,0,1]
	v_lshl_add_u64 v[236:237], v[230:231], 0, s[20:21]
	v_lshl_add_u64 v[234:235], v[230:231], 0, s[22:23]
	v_lshl_add_u64 v[244:245], v[228:229], 0, v[234:235]
	v_lshl_add_u64 v[250:251], s[34:35], 0, v[202:203]
	v_pk_fma_f32 v[96:97], v[96:97], 0.5, v[180:181] op_sel_hi:[1,0,1]
	v_pk_fma_f32 v[94:95], v[94:95], 0.5, v[178:179] op_sel_hi:[1,0,1]
	v_pk_fma_f32 v[88:89], v[88:89], 0.5, v[172:173] op_sel_hi:[1,0,1]
	v_pk_fma_f32 v[86:87], v[86:87], 0.5, v[170:171] op_sel_hi:[1,0,1]
	v_pk_fma_f32 v[84:85], v[84:85], 0.5, v[164:165] op_sel_hi:[1,0,1]
	v_pk_fma_f32 v[82:83], v[82:83], 0.5, v[162:163] op_sel_hi:[1,0,1]
	v_pk_fma_f32 v[80:81], v[80:81], 0.5, v[156:157] op_sel_hi:[1,0,1]
	v_pk_fma_f32 v[78:79], v[78:79], 0.5, v[154:155] op_sel_hi:[1,0,1]
	v_pk_fma_f32 v[76:77], v[76:77], 0.5, v[148:149] op_sel_hi:[1,0,1]
	v_pk_fma_f32 v[74:75], v[74:75], 0.5, v[146:147] op_sel_hi:[1,0,1]
	v_pk_fma_f32 v[72:73], v[72:73], 0.5, v[136:137] op_sel_hi:[1,0,1]
	v_pk_fma_f32 v[70:71], v[70:71], 0.5, v[134:135] op_sel_hi:[1,0,1]
	v_pk_fma_f32 v[132:133], v[68:69], 0.5, v[132:133] op_sel_hi:[1,0,1]
	v_pk_fma_f32 v[130:131], v[66:67], 0.5, v[130:131] op_sel_hi:[1,0,1]
	s_waitcnt vmcnt(0)
	v_pk_mul_f32 v[160:161], v[92:93], v[160:161]
	v_pk_mul_f32 v[158:159], v[90:91], v[158:159]
	s_nop 0
	v_cvt_pk_bf16_f32 v158, v158, v159
	v_cvt_pk_bf16_f32 v159, v160, v161
	global_load_dwordx4 v[218:221], v[224:225], off offset:64
	global_store_dwordx2 v[252:253], v[158:159], off
	global_store_dwordx4 v[248:249], v[98:101], off offset:64
	s_waitcnt vmcnt(2)
; #define ER_LOAD(q, buf) do { _Pragma("unroll") for (int mm = 0; mm < 2; ++mm) { const size_t off_ = (size_t)(row0 + ((q) >> 1) * HALF + (2 * ((q) & 1) + mm) * 16) * ldc + col0; \
;             _Pragma("unroll") for (int bj = 0; bj < 2; ++bj) _Pragma("unroll") for (int n = 0; n < 2; ++n) pre[buf][mm][bj][n] = *(const f32x4*)(base + off_ + bj * HALF + n * 16); } } while (0)
;     __device__ __forceinline__ void operator()(const f32x4 (&acc)[2][2][4][2], const Unit& u, int wr, int wc, int fr, int fq) const {
;         const int row0 = u.pm * BM + wr * 64 + fr, col0 = u.pn * BM + wc * 32 + 4 * fq;
;         bf16_t* XB = (bf16_t*)(ws + XBOFF); float* stat = (float*)(ws + STOFF); const float* gain = (const float*)(ws + GOFF);
;         typedef unsigned u32x2_ __attribute__((ext_vector_type(2)));
;         f32x4 pre[2][2][2][2]; float ssq[8];
;     ...
;         ER_LOAD(0, 0);
; #pragma unroll
;         for (int q = 0; q < 4; ++q) {
;             if (q == 0) ER_LOAD(1, 1); else if (q == 1) ER_LOAD(2, 0); else if (q == 2) ER_LOAD(3, 1);
; #pragma unroll
;             for (int mm = 0; mm < 2; ++mm) { const int ai = q >> 1, m = 2 * (q & 1) + mm; const size_t off = (size_t)(row0 + ai * HALF + m * 16) * ldc + col0; float ss = 0.f;
;                 const int rl = wr * 64 + fr + ai * HALF + m * 16, cl0 = col0; const size_t xoff = (size_t)u.pm * ((size_t)ldc * BM) + (size_t)rl * 64;
; #pragma unroll
;                 for (int bj = 0; bj < 2; ++bj)
; #pragma unroll
;                     for (int n = 0; n < 2; ++n) {
;                         const f32x4 o = pre[q & 1][mm][bj][n] + acc[ai][bj][m][n] * scale;
;                         *(f32x4*)(out + off + bj * HALF + n * 16) = o;
;                         if (COPY) { const f32x4 gn = *(const f32x4*)(gain + col0 + bj * HALF + n * 16); u32x2_ w; w.x = pk_bf16(o[0] * gn[0], o[1] * gn[1]); w.y = pk_bf16(o[2] * gn[2], o[3] * gn[3]); *(u32x2_*)(XB + xoff + (size_t)((cl0 + bj * HALF + n * 16) >> 6) * (256 * 64) + ((cl0 + bj * HALF + n * 16) & 63)) = w; ss += (o[0] * o[0] + o[1] * o[1]) + (o[2] * o[2] + o[3] * o[3]); } }
;                 if (COPY) { ss += __shfl_xor(ss, 16); ss += __shfl_xor(ss, 32); ssq[2 * q + mm] = ss; } }
;         }
	v_pk_mul_f32 v[160:161], v[100:101], v[220:221]
	v_pk_mul_f32 v[158:159], v[98:99], v[218:219]
	v_mul_f32_e32 v99, v99, v99
	v_cvt_pk_bf16_f32 v158, v158, v159
	v_cvt_pk_bf16_f32 v159, v160, v161
	global_load_dwordx4 v[218:221], v[224:225], off offset:512
	global_store_dwordx2 v[252:253], v[158:159], off offset:32
	global_store_dwordx4 v[248:249], v[106:109], off offset:512
	v_lshl_add_u64 v[252:253], v[250:251], 0, s[36:37]
	v_lshl_add_u64 v[252:253], v[252:253], 0, v[194:195]
	v_mul_f32_e32 v101, v101, v101
	v_fmac_f32_e32 v99, v98, v98
	v_fmac_f32_e32 v101, v100, v100
	s_waitcnt vmcnt(2)
	v_pk_mul_f32 v[160:161], v[108:109], v[220:221]
	v_pk_mul_f32 v[158:159], v[106:107], v[218:219]
	v_mul_f32_e32 v107, v107, v107
	v_cvt_pk_bf16_f32 v158, v158, v159
	v_cvt_pk_bf16_f32 v159, v160, v161
	global_load_dwordx4 v[218:221], v[224:225], off offset:576
	global_store_dwordx2 v[166:167], v[158:159], off
	global_store_dwordx4 v[248:249], v[114:117], off offset:576
	v_lshl_add_u64 v[248:249], v[150:151], 0, v[226:227]
	v_lshl_add_u64 v[150:151], v[228:229], 0, v[236:237]
	v_mul_f32_e32 v109, v109, v109
	v_fmac_f32_e32 v107, v106, v106
	v_fmac_f32_e32 v109, v108, v108
	s_waitcnt vmcnt(2)
	v_pk_mul_f32 v[160:161], v[116:117], v[220:221]
	v_pk_mul_f32 v[158:159], v[114:115], v[218:219]
	v_mul_f32_e32 v115, v115, v115
	v_cvt_pk_bf16_f32 v158, v158, v159
	v_cvt_pk_bf16_f32 v159, v160, v161
	global_load_dwordx4 v[218:221], v[224:225], off
	global_store_dwordx2 v[166:167], v[158:159], off offset:32
	global_store_dwordx4 v[152:153], v[122:125], off
	v_lshl_add_u64 v[166:167], s[34:35], 0, v[200:201]
	v_lshl_add_u64 v[168:169], v[166:167], 0, s[36:37]
	v_lshl_add_u64 v[168:169], v[168:169], 0, v[194:195]
	v_lshl_add_u64 v[166:167], v[166:167], 0, s[38:39]
	v_lshl_add_u64 v[166:167], v[166:167], 0, v[194:195]
	v_mul_f32_e32 v117, v117, v117
	v_fmac_f32_e32 v115, v114, v114
	v_fmac_f32_e32 v117, v116, v116
	s_waitcnt vmcnt(2)
	v_pk_mul_f32 v[160:161], v[124:125], v[220:221]
	v_pk_mul_f32 v[158:159], v[122:123], v[218:219]
	v_mul_f32_e32 v123, v123, v123
	v_cvt_pk_bf16_f32 v158, v158, v159
	v_cvt_pk_bf16_f32 v159, v160, v161
	global_load_dwordx4 v[218:221], v[224:225], off offset:64
	global_store_dwordx2 v[168:169], v[158:159], off
	global_store_dwordx4 v[152:153], v[126:129], off offset:64
	v_mul_f32_e32 v125, v125, v125
	v_fmac_f32_e32 v123, v122, v122
	v_fmac_f32_e32 v125, v124, v124
	s_waitcnt vmcnt(2)
	v_pk_mul_f32 v[160:161], v[128:129], v[220:221]
	v_pk_mul_f32 v[158:159], v[126:127], v[218:219]
	v_mul_f32_e32 v127, v127, v127
	v_cvt_pk_bf16_f32 v158, v158, v159
	v_cvt_pk_bf16_f32 v159, v160, v161
	global_load_dwordx4 v[218:221], v[224:225], off offset:512
	global_store_dwordx2 v[168:169], v[158:159], off offset:32
	global_store_dwordx4 v[152:153], v[118:121], off offset:512
	v_mul_f32_e32 v129, v129, v129
	v_fmac_f32_e32 v127, v126, v126
	v_fmac_f32_e32 v129, v128, v128
	s_waitcnt vmcnt(2)
	v_pk_mul_f32 v[142:143], v[120:121], v[220:221]
	v_pk_mul_f32 v[144:145], v[118:119], v[218:219]
	v_mul_f32_e32 v119, v119, v119
	v_cvt_pk_bf16_f32 v144, v144, v145
	v_cvt_pk_bf16_f32 v145, v142, v143
	global_load_dwordx4 v[218:221], v[224:225], off offset:576
	global_store_dwordx2 v[166:167], v[144:145], off
	global_store_dwordx4 v[152:153], v[110:113], off offset:576
	v_mul_f32_e32 v121, v121, v121
	v_fmac_f32_e32 v119, v118, v118
	v_fmac_f32_e32 v121, v120, v120
	s_waitcnt vmcnt(2)
	v_pk_mul_f32 v[138:139], v[112:113], v[220:221]
	v_pk_mul_f32 v[140:141], v[110:111], v[218:219]
	v_mul_f32_e32 v111, v111, v111
	v_cvt_pk_bf16_f32 v140, v140, v141
	v_cvt_pk_bf16_f32 v141, v138, v139
	global_store_dwordx2 v[166:167], v[140:141], off offset:32
	global_load_dwordx4 v[186:189], v[150:151], off
	global_load_dwordx4 v[182:185], v[150:151], off offset:64
	global_load_dwordx4 v[174:177], v[150:151], off offset:512
	s_nop 0
	global_load_dwordx4 v[166:169], v[150:151], off offset:576
	global_load_dwordx4 v[158:161], v[244:245], off
	s_nop 0
	global_load_dwordx4 v[150:153], v[244:245], off offset:64
	global_load_dwordx4 v[142:145], v[244:245], off offset:512
	global_load_dwordx4 v[138:141], v[244:245], off offset:576
	v_mul_f32_e32 v113, v113, v113
	global_store_dwordx4 v[248:249], v[102:105], off
	global_load_dwordx4 v[244:247], v[224:225], off
	v_fmac_f32_e32 v111, v110, v110
	v_fmac_f32_e32 v113, v112, v112
	s_waitcnt vmcnt(8)
	v_pk_fma_f32 v[60:61], v[60:61], 0.5, v[184:185] op_sel_hi:[1,0,1]
	v_pk_fma_f32 v[58:59], v[58:59], 0.5, v[182:183] op_sel_hi:[1,0,1]
	s_waitcnt vmcnt(7)
	v_pk_fma_f32 v[56:57], v[56:57], 0.5, v[176:177] op_sel_hi:[1,0,1]
	v_pk_fma_f32 v[54:55], v[54:55], 0.5, v[174:175] op_sel_hi:[1,0,1]
	s_waitcnt vmcnt(6)
	v_pk_fma_f32 v[52:53], v[52:53], 0.5, v[168:169] op_sel_hi:[1,0,1]
	v_pk_fma_f32 v[50:51], v[50:51], 0.5, v[166:167] op_sel_hi:[1,0,1]
	s_waitcnt vmcnt(5)
	v_pk_fma_f32 v[48:49], v[48:49], 0.5, v[160:161] op_sel_hi:[1,0,1]
	v_pk_fma_f32 v[46:47], v[46:47], 0.5, v[158:159] op_sel_hi:[1,0,1]
	s_waitcnt vmcnt(4)
	v_pk_fma_f32 v[44:45], v[44:45], 0.5, v[152:153] op_sel_hi:[1,0,1]
	s_waitcnt vmcnt(0)
	v_pk_mul_f32 v[178:179], v[104:105], v[246:247]
	v_pk_mul_f32 v[180:181], v[102:103], v[244:245]
	v_pk_fma_f32 v[42:43], v[42:43], 0.5, v[150:151] op_sel_hi:[1,0,1]
	v_cvt_pk_bf16_f32 v180, v180, v181
	v_cvt_pk_bf16_f32 v181, v178, v179
	global_load_dwordx4 v[218:221], v[224:225], off offset:64
	global_store_dwordx2 v[252:253], v[180:181], off
	global_store_dwordx4 v[248:249], v[94:97], off offset:64
	v_pk_fma_f32 v[40:41], v[40:41], 0.5, v[144:145] op_sel_hi:[1,0,1]
	v_pk_fma_f32 v[38:39], v[38:39], 0.5, v[142:143] op_sel_hi:[1,0,1]
	v_pk_fma_f32 v[36:37], v[36:37], 0.5, v[140:141] op_sel_hi:[1,0,1]
	v_pk_fma_f32 v[34:35], v[34:35], 0.5, v[138:139] op_sel_hi:[1,0,1]
	v_mul_f32_e32 v103, v103, v103
	v_mul_f32_e32 v105, v105, v105
	v_fmac_f32_e32 v103, v102, v102
	v_fmac_f32_e32 v105, v104, v104
	s_waitcnt vmcnt(2)
; #define ER_LOAD(q, buf) do { _Pragma("unroll") for (int mm = 0; mm < 2; ++mm) { const size_t off_ = (size_t)(row0 + ((q) >> 1) * HALF + (2 * ((q) & 1) + mm) * 16) * ldc + col0; \
;             _Pragma("unroll") for (int bj = 0; bj < 2; ++bj) _Pragma("unroll") for (int n = 0; n < 2; ++n) pre[buf][mm][bj][n] = *(const f32x4*)(base + off_ + bj * HALF + n * 16); } } while (0)
;     __device__ __forceinline__ void operator()(const f32x4 (&acc)[2][2][4][2], const Unit& u, int wr, int wc, int fr, int fq) const {
;         const int row0 = u.pm * BM + wr * 64 + fr, col0 = u.pn * BM + wc * 32 + 4 * fq;
;         bf16_t* XB = (bf16_t*)(ws + XBOFF); float* stat = (float*)(ws + STOFF); const float* gain = (const float*)(ws + GOFF);
;         typedef unsigned u32x2_ __attribute__((ext_vector_type(2)));
;         f32x4 pre[2][2][2][2]; float ssq[8];
;     ...
;         ER_LOAD(0, 0);
; #pragma unroll
;         for (int q = 0; q < 4; ++q) {
;             if (q == 0) ER_LOAD(1, 1); else if (q == 1) ER_LOAD(2, 0); else if (q == 2) ER_LOAD(3, 1);
; #pragma unroll
;             for (int mm = 0; mm < 2; ++mm) { const int ai = q >> 1, m = 2 * (q & 1) + mm; const size_t off = (size_t)(row0 + ai * HALF + m * 16) * ldc + col0; float ss = 0.f;
;                 const int rl = wr * 64 + fr + ai * HALF + m * 16, cl0 = col0; const size_t xoff = (size_t)u.pm * ((size_t)ldc * BM) + (size_t)rl * 64;
; #pragma unroll
;                 for (int bj = 0; bj < 2; ++bj)
; #pragma unroll
;                     for (int n = 0; n < 2; ++n) {
;                         const f32x4 o = pre[q & 1][mm][bj][n] + acc[ai][bj][m][n] * scale;
;                         *(f32x4*)(out + off + bj * HALF + n * 16) = o;
;                         if (COPY) { const f32x4 gn = *(const f32x4*)(gain + col0 + bj * HALF + n * 16); u32x2_ w; w.x = pk_bf16(o[0] * gn[0], o[1] * gn[1]); w.y = pk_bf16(o[2] * gn[2], o[3] * gn[3]); *(u32x2_*)(XB + xoff + (size_t)((cl0 + bj * HALF + n * 16) >> 6) * (256 * 64) + ((cl0 + bj * HALF + n * 16) & 63)) = w; ss += (o[0] * o[0] + o[1] * o[1]) + (o[2] * o[2] + o[3] * o[3]); } }
;                 if (COPY) { ss += __shfl_xor(ss, 16); ss += __shfl_xor(ss, 32); ssq[2 * q + mm] = ss; } }
;         }
	v_pk_mul_f32 v[170:171], v[96:97], v[220:221]
	v_pk_mul_f32 v[172:173], v[94:95], v[218:219]
	v_lshl_add_u64 v[178:179], v[250:251], 0, s[38:39]
	v_cvt_pk_bf16_f32 v172, v172, v173
	v_cvt_pk_bf16_f32 v173, v170, v171
	global_load_dwordx4 v[218:221], v[224:225], off offset:512
	global_store_dwordx2 v[252:253], v[172:173], off offset:32
	global_store_dwordx4 v[248:249], v[86:89], off offset:512
	v_lshl_add_u64 v[178:179], v[178:179], 0, v[194:195]
	s_waitcnt vmcnt(2)
	v_pk_mul_f32 v[162:163], v[88:89], v[220:221]
	v_pk_mul_f32 v[164:165], v[86:87], v[218:219]
	v_lshl_add_u64 v[170:171], s[48:49], 0, v[232:233]
	v_cvt_pk_bf16_f32 v164, v164, v165
	v_cvt_pk_bf16_f32 v165, v162, v163
	global_load_dwordx4 v[218:221], v[224:225], off offset:576
	global_store_dwordx2 v[178:179], v[164:165], off
	global_store_dwordx4 v[248:249], v[82:85], off offset:576
	v_lshl_add_u64 v[170:171], v[170:171], 0, v[226:227]
	v_lshl_add_u64 v[232:233], v[230:231], 0, s[26:27]
	v_lshl_add_u64 v[230:231], v[230:231], 0, s[28:29]
	v_mul_f32_e32 v87, v87, v87
	v_mul_f32_e32 v89, v89, v89
	v_fmac_f32_e32 v87, v86, v86
	v_fmac_f32_e32 v89, v88, v88
	s_waitcnt vmcnt(2)
	v_pk_mul_f32 v[154:155], v[84:85], v[220:221]
	v_pk_mul_f32 v[156:157], v[82:83], v[218:219]
	v_lshl_add_u64 v[162:163], s[34:35], 0, v[204:205]
	v_cvt_pk_bf16_f32 v156, v156, v157
	v_cvt_pk_bf16_f32 v157, v154, v155
	global_load_dwordx4 v[218:221], v[224:225], off
	global_store_dwordx2 v[178:179], v[156:157], off offset:32
	global_store_dwordx4 v[170:171], v[78:81], off
	v_lshl_add_u64 v[164:165], v[162:163], 0, s[36:37]
	v_lshl_add_u64 v[164:165], v[164:165], 0, v[194:195]
	v_mul_f32_e32 v83, v83, v83
	v_mul_f32_e32 v85, v85, v85
	v_fmac_f32_e32 v83, v82, v82
	v_fmac_f32_e32 v85, v84, v84
	v_add_f32_e32 v82, v87, v89
	v_add_f32_e32 v83, v83, v85
	s_waitcnt vmcnt(2)
	v_pk_mul_f32 v[146:147], v[80:81], v[220:221]
	v_pk_mul_f32 v[148:149], v[78:79], v[218:219]
	v_mul_f32_e32 v79, v79, v79
	v_cvt_pk_bf16_f32 v148, v148, v149
	v_cvt_pk_bf16_f32 v149, v146, v147
	global_load_dwordx4 v[218:221], v[224:225], off offset:64
	global_store_dwordx2 v[164:165], v[148:149], off
	global_store_dwordx4 v[170:171], v[74:77], off offset:64
	v_mul_f32_e32 v81, v81, v81
	v_fmac_f32_e32 v79, v78, v78
	v_fmac_f32_e32 v81, v80, v80
	v_add_f32_e32 v78, v103, v105
	v_add_f32_e32 v79, v79, v81
	s_waitcnt vmcnt(2)
	v_pk_mul_f32 v[134:135], v[76:77], v[220:221]
	v_pk_mul_f32 v[136:137], v[74:75], v[218:219]
	v_lshl_add_u64 v[146:147], v[162:163], 0, s[38:39]
	v_cvt_pk_bf16_f32 v136, v136, v137
	v_cvt_pk_bf16_f32 v137, v134, v135
	global_load_dwordx4 v[218:221], v[224:225], off offset:512
	global_store_dwordx2 v[164:165], v[136:137], off offset:32
	global_store_dwordx4 v[170:171], v[70:73], off offset:512
	v_lshl_add_u64 v[146:147], v[146:147], 0, v[194:195]
	v_lshl_add_u64 v[148:149], v[228:229], 0, v[232:233]
	v_lshl_add_u64 v[228:229], v[228:229], 0, v[230:231]
	v_mul_f32_e32 v75, v75, v75
	v_mul_f32_e32 v77, v77, v77
	v_fmac_f32_e32 v75, v74, v74
	v_fmac_f32_e32 v77, v76, v76
	v_add_f32_e32 v75, v75, v77
	v_add_f32_e32 v74, v119, v121
	v_add_f32_e32 v76, v111, v113
	v_mul_f32_e32 v77, v57, v57
	v_fmac_f32_e32 v77, v56, v56
	s_waitcnt vmcnt(2)
	v_pk_mul_f32 v[66:67], v[72:73], v[220:221]
	v_pk_mul_f32 v[68:69], v[70:71], v[218:219]
	v_mul_f32_e32 v71, v71, v71
	v_cvt_pk_bf16_f32 v68, v68, v69
	v_cvt_pk_bf16_f32 v69, v66, v67
	global_load_dwordx4 v[218:221], v[224:225], off offset:576
	global_store_dwordx2 v[146:147], v[68:69], off
	global_store_dwordx4 v[170:171], v[130:133], off offset:576
	v_lshl_add_u64 v[66:67], s[48:49], 0, v[236:237]
	v_lshl_add_u64 v[236:237], v[66:67], 0, v[226:227]
	v_pk_fma_f32 v[68:69], v[64:65], 0.5, v[188:189] op_sel_hi:[1,0,1]
	v_pk_fma_f32 v[66:67], v[62:63], 0.5, v[186:187] op_sel_hi:[1,0,1]
	v_mul_f32_e32 v73, v73, v73
	v_fmac_f32_e32 v71, v70, v70
	v_fmac_f32_e32 v73, v72, v72
	v_add_f32_e32 v70, v123, v125
	v_add_f32_e32 v72, v127, v129
	v_add_f32_e32 v71, v71, v73
	s_waitcnt vmcnt(2)
	v_pk_mul_f32 v[62:63], v[132:133], v[220:221]
	v_pk_mul_f32 v[64:65], v[130:131], v[218:219]
	v_mul_f32_e32 v131, v131, v131
	v_cvt_pk_bf16_f32 v64, v64, v65
	v_cvt_pk_bf16_f32 v65, v62, v63
	global_store_dwordx2 v[146:147], v[64:65], off offset:32
	global_load_dwordx4 v[186:189], v[148:149], off
	global_load_dwordx4 v[178:181], v[148:149], off offset:64
	global_load_dwordx4 v[170:173], v[148:149], off offset:512
	global_load_dwordx4 v[162:165], v[148:149], off offset:576
	global_load_dwordx4 v[154:157], v[228:229], off
	s_nop 0
	global_load_dwordx4 v[146:149], v[228:229], off offset:64
	global_load_dwordx4 v[134:137], v[228:229], off offset:512
	global_load_dwordx4 v[62:65], v[228:229], off offset:576
	v_lshl_add_u64 v[228:229], s[34:35], 0, v[206:207]
	global_store_dwordx4 v[236:237], v[66:69], off
	global_load_dwordx4 v[244:247], v[224:225], off
	v_lshl_add_u64 v[248:249], v[228:229], 0, s[36:37]
	v_lshl_add_u64 v[248:249], v[248:249], 0, v[194:195]
	v_mul_f32_e32 v133, v133, v133
	v_fmac_f32_e32 v131, v130, v130
	v_fmac_f32_e32 v133, v132, v132
	v_add_f32_e32 v73, v131, v133
	s_waitcnt vmcnt(9)
	v_pk_fma_f32 v[32:33], v[32:33], 0.5, v[188:189] op_sel_hi:[1,0,1]
	v_pk_fma_f32 v[30:31], v[30:31], 0.5, v[186:187] op_sel_hi:[1,0,1]
	s_waitcnt vmcnt(8)
	v_pk_fma_f32 v[28:29], v[28:29], 0.5, v[180:181] op_sel_hi:[1,0,1]
	v_pk_fma_f32 v[26:27], v[26:27], 0.5, v[178:179] op_sel_hi:[1,0,1]
	s_waitcnt vmcnt(7)
	v_pk_fma_f32 v[24:25], v[24:25], 0.5, v[172:173] op_sel_hi:[1,0,1]
	v_pk_fma_f32 v[22:23], v[22:23], 0.5, v[170:171] op_sel_hi:[1,0,1]
	s_waitcnt vmcnt(6)
; #define ER_LOAD(q, buf) do { _Pragma("unroll") for (int mm = 0; mm < 2; ++mm) { const size_t off_ = (size_t)(row0 + ((q) >> 1) * HALF + (2 * ((q) & 1) + mm) * 16) * ldc + col0; \
;             _Pragma("unroll") for (int bj = 0; bj < 2; ++bj) _Pragma("unroll") for (int n = 0; n < 2; ++n) pre[buf][mm][bj][n] = *(const f32x4*)(base + off_ + bj * HALF + n * 16); } } while (0)
;     __device__ __forceinline__ void operator()(const f32x4 (&acc)[2][2][4][2], const Unit& u, int wr, int wc, int fr, int fq) const {
;         const int row0 = u.pm * BM + wr * 64 + fr, col0 = u.pn * BM + wc * 32 + 4 * fq;
;         bf16_t* XB = (bf16_t*)(ws + XBOFF); float* stat = (float*)(ws + STOFF); const float* gain = (const float*)(ws + GOFF);
;         typedef unsigned u32x2_ __attribute__((ext_vector_type(2)));
;         f32x4 pre[2][2][2][2]; float ssq[8];
;     ...
;         ER_LOAD(0, 0);
; #pragma unroll
;         for (int q = 0; q < 4; ++q) {
;             if (q == 0) ER_LOAD(1, 1); else if (q == 1) ER_LOAD(2, 0); else if (q == 2) ER_LOAD(3, 1);
; #pragma unroll
;             for (int mm = 0; mm < 2; ++mm) { const int ai = q >> 1, m = 2 * (q & 1) + mm; const size_t off = (size_t)(row0 + ai * HALF + m * 16) * ldc + col0; float ss = 0.f;
;                 const int rl = wr * 64 + fr + ai * HALF + m * 16, cl0 = col0; const size_t xoff = (size_t)u.pm * ((size_t)ldc * BM) + (size_t)rl * 64;
; #pragma unroll
;                 for (int bj = 0; bj < 2; ++bj)
; #pragma unroll
;                     for (int n = 0; n < 2; ++n) {
;                         const f32x4 o = pre[q & 1][mm][bj][n] + acc[ai][bj][m][n] * scale;
;                         *(f32x4*)(out + off + bj * HALF + n * 16) = o;
;                         if (COPY) { const f32x4 gn = *(const f32x4*)(gain + col0 + bj * HALF + n * 16); u32x2_ w; w.x = pk_bf16(o[0] * gn[0], o[1] * gn[1]); w.y = pk_bf16(o[2] * gn[2], o[3] * gn[3]); *(u32x2_*)(XB + xoff + (size_t)((cl0 + bj * HALF + n * 16) >> 6) * (256 * 64) + ((cl0 + bj * HALF + n * 16) & 63)) = w; ss += (o[0] * o[0] + o[1] * o[1]) + (o[2] * o[2] + o[3] * o[3]); } }
;                 if (COPY) { ss += __shfl_xor(ss, 16); ss += __shfl_xor(ss, 32); ssq[2 * q + mm] = ss; } }
;         }
	v_pk_fma_f32 v[20:21], v[20:21], 0.5, v[164:165] op_sel_hi:[1,0,1]
	v_pk_fma_f32 v[18:19], v[18:19], 0.5, v[162:163] op_sel_hi:[1,0,1]
	s_waitcnt vmcnt(5)
	v_pk_fma_f32 v[16:17], v[16:17], 0.5, v[156:157] op_sel_hi:[1,0,1]
	v_pk_fma_f32 v[14:15], v[14:15], 0.5, v[154:155] op_sel_hi:[1,0,1]
	s_waitcnt vmcnt(0)
	v_pk_mul_f32 v[182:183], v[68:69], v[246:247]
	v_pk_mul_f32 v[184:185], v[66:67], v[244:245]
	v_pk_fma_f32 v[12:13], v[12:13], 0.5, v[148:149] op_sel_hi:[1,0,1]
	v_cvt_pk_bf16_f32 v184, v184, v185
	v_cvt_pk_bf16_f32 v185, v182, v183
	global_load_dwordx4 v[218:221], v[224:225], off offset:64
	global_store_dwordx2 v[248:249], v[184:185], off
	global_store_dwordx4 v[236:237], v[58:61], off offset:64
	v_pk_fma_f32 v[10:11], v[10:11], 0.5, v[146:147] op_sel_hi:[1,0,1]
	v_and_b32_e32 v147, 64, v242
	v_xor_b32_e32 v146, 16, v242
	v_add_u32_e32 v147, 64, v147
	v_xor_b32_e32 v148, 32, v242
	v_cmp_lt_i32_e32 vcc, v146, v147
	v_mul_f32_e32 v149, v93, v93
	v_fmac_f32_e32 v149, v92, v92
	v_cndmask_b32_e32 v146, v242, v146, vcc
	v_cmp_lt_i32_e32 vcc, v148, v147
	v_pk_fma_f32 v[92:93], v[8:9], 0.5, v[136:137] op_sel_hi:[1,0,1]
	v_mul_f32_e32 v67, v67, v67
	v_cndmask_b32_e32 v147, v242, v148, vcc
	v_mul_f32_e32 v148, v91, v91
	v_fmac_f32_e32 v148, v90, v90
	v_pk_fma_f32 v[90:91], v[6:7], 0.5, v[134:135] op_sel_hi:[1,0,1]
	v_mul_f32_e32 v69, v69, v69
	v_fmac_f32_e32 v67, v66, v66
	v_fmac_f32_e32 v69, v68, v68
	v_lshlrev_b32_e32 v146, 2, v146
	v_lshlrev_b32_e32 v147, 2, v147
	s_waitcnt vmcnt(2)
	v_pk_mul_f32 v[174:175], v[60:61], v[220:221]
	v_pk_mul_f32 v[176:177], v[58:59], v[218:219]
	v_lshl_add_u64 v[182:183], v[228:229], 0, s[38:39]
	v_cvt_pk_bf16_f32 v176, v176, v177
	v_cvt_pk_bf16_f32 v177, v174, v175
	global_load_dwordx4 v[218:221], v[224:225], off offset:512
	global_store_dwordx2 v[248:249], v[176:177], off offset:32
	global_store_dwordx4 v[236:237], v[54:57], off offset:512
	v_lshl_add_u64 v[182:183], v[182:183], 0, v[194:195]
	v_mul_f32_e32 v59, v59, v59
	v_mul_f32_e32 v61, v61, v61
	v_fmac_f32_e32 v59, v58, v58
	v_fmac_f32_e32 v61, v60, v60
	s_waitcnt vmcnt(2)
	v_pk_mul_f32 v[166:167], v[56:57], v[220:221]
	v_pk_mul_f32 v[168:169], v[54:55], v[218:219]
	v_lshl_add_u64 v[174:175], s[48:49], 0, v[234:235]
	v_cvt_pk_bf16_f32 v168, v168, v169
	v_cvt_pk_bf16_f32 v169, v166, v167
	global_load_dwordx4 v[218:221], v[224:225], off offset:576
	global_store_dwordx2 v[182:183], v[168:169], off
	global_store_dwordx4 v[236:237], v[50:53], off offset:576
	v_lshl_add_u64 v[174:175], v[174:175], 0, v[226:227]
	s_waitcnt vmcnt(2)
	v_pk_mul_f32 v[158:159], v[52:53], v[220:221]
	v_pk_mul_f32 v[160:161], v[50:51], v[218:219]
	v_lshl_add_u64 v[166:167], s[34:35], 0, v[208:209]
	v_cvt_pk_bf16_f32 v160, v160, v161
	v_cvt_pk_bf16_f32 v161, v158, v159
	global_load_dwordx4 v[218:221], v[224:225], off
	global_store_dwordx2 v[182:183], v[160:161], off offset:32
	global_store_dwordx4 v[174:175], v[46:49], off
	v_lshl_add_u64 v[168:169], v[166:167], 0, s[36:37]
	v_lshl_add_u64 v[168:169], v[168:169], 0, v[194:195]
	s_waitcnt vmcnt(2)
	v_pk_mul_f32 v[150:151], v[48:49], v[220:221]
	v_pk_mul_f32 v[152:153], v[46:47], v[218:219]
	v_mul_f32_e32 v47, v47, v47
	v_cvt_pk_bf16_f32 v152, v152, v153
	v_cvt_pk_bf16_f32 v153, v150, v151
	global_load_dwordx4 v[218:221], v[224:225], off offset:64
	global_store_dwordx2 v[168:169], v[152:153], off
	global_store_dwordx4 v[174:175], v[42:45], off offset:64
	v_mul_f32_e32 v49, v49, v49
	v_fmac_f32_e32 v47, v46, v46
	v_fmac_f32_e32 v49, v48, v48
	s_waitcnt vmcnt(2)
	v_pk_mul_f32 v[142:143], v[44:45], v[220:221]
	v_pk_mul_f32 v[144:145], v[42:43], v[218:219]
	v_lshl_add_u64 v[150:151], v[166:167], 0, s[38:39]
	v_cvt_pk_bf16_f32 v144, v144, v145
	v_cvt_pk_bf16_f32 v145, v142, v143
	global_load_dwordx4 v[218:221], v[224:225], off offset:512
	global_store_dwordx2 v[168:169], v[144:145], off offset:32
	global_store_dwordx4 v[174:175], v[38:41], off offset:512
	v_lshl_add_u64 v[150:151], v[150:151], 0, v[194:195]
	v_mul_f32_e32 v152, v95, v95
	v_mul_f32_e32 v153, v97, v97
	v_fmac_f32_e32 v152, v94, v94
	v_fmac_f32_e32 v153, v96, v96
	v_add_f32_e32 v80, v152, v153
	v_mul_f32_e32 v43, v43, v43
	v_mul_f32_e32 v45, v45, v45
	v_fmac_f32_e32 v43, v42, v42
	v_fmac_f32_e32 v45, v44, v44
	s_waitcnt vmcnt(2)
	v_pk_mul_f32 v[138:139], v[40:41], v[220:221]
	v_pk_mul_f32 v[140:141], v[38:39], v[218:219]
	v_lshl_add_u64 v[142:143], s[48:49], 0, v[232:233]
	v_cvt_pk_bf16_f32 v140, v140, v141
	v_cvt_pk_bf16_f32 v141, v138, v139
	global_load_dwordx4 v[218:221], v[224:225], off offset:576
	global_store_dwordx2 v[150:151], v[140:141], off
	global_store_dwordx4 v[174:175], v[34:37], off offset:576
	v_lshl_add_u64 v[142:143], v[142:143], 0, v[226:227]
	v_lshl_add_u64 v[144:145], s[34:35], 0, v[210:211]
	v_mul_f32_e32 v39, v39, v39
	v_mul_f32_e32 v41, v41, v41
	v_fmac_f32_e32 v39, v38, v38
	v_fmac_f32_e32 v41, v40, v40
	v_add_f32_e32 v38, v39, v41
	s_waitcnt vmcnt(2)
	v_pk_mul_f32 v[140:141], v[36:37], v[220:221]
	v_pk_mul_f32 v[138:139], v[34:35], v[218:219]
	v_mul_f32_e32 v35, v35, v35
	v_cvt_pk_bf16_f32 v138, v138, v139
	v_cvt_pk_bf16_f32 v139, v140, v141
	global_load_dwordx4 v[218:221], v[224:225], off
	global_store_dwordx2 v[150:151], v[138:139], off offset:32
	global_store_dwordx4 v[142:143], v[30:33], off
	v_lshl_add_u64 v[150:151], v[144:145], 0, s[36:37]
	v_lshl_add_u64 v[150:151], v[150:151], 0, v[194:195]
	v_lshl_add_u64 v[144:145], v[144:145], 0, s[38:39]
	v_lshl_add_u64 v[144:145], v[144:145], 0, v[194:195]
	v_mul_f32_e32 v37, v37, v37
	v_fmac_f32_e32 v35, v34, v34
	v_fmac_f32_e32 v37, v36, v36
	v_add_f32_e32 v34, v47, v49
	v_add_f32_e32 v36, v43, v45
	v_add_f32_e32 v35, v35, v37
	s_waitcnt vmcnt(2)
; #define ER_LOAD(q, buf) do { _Pragma("unroll") for (int mm = 0; mm < 2; ++mm) { const size_t off_ = (size_t)(row0 + ((q) >> 1) * HALF + (2 * ((q) & 1) + mm) * 16) * ldc + col0; \
;             _Pragma("unroll") for (int bj = 0; bj < 2; ++bj) _Pragma("unroll") for (int n = 0; n < 2; ++n) pre[buf][mm][bj][n] = *(const f32x4*)(base + off_ + bj * HALF + n * 16); } } while (0)
;     __device__ __forceinline__ void operator()(const f32x4 (&acc)[2][2][4][2], const Unit& u, int wr, int wc, int fr, int fq) const {
;         const int row0 = u.pm * BM + wr * 64 + fr, col0 = u.pn * BM + wc * 32 + 4 * fq;
;         bf16_t* XB = (bf16_t*)(ws + XBOFF); float* stat = (float*)(ws + STOFF); const float* gain = (const float*)(ws + GOFF);
;         typedef unsigned u32x2_ __attribute__((ext_vector_type(2)));
;         f32x4 pre[2][2][2][2]; float ssq[8];
;     ...
;         ER_LOAD(0, 0);
; #pragma unroll
;         for (int q = 0; q < 4; ++q) {
;             if (q == 0) ER_LOAD(1, 1); else if (q == 1) ER_LOAD(2, 0); else if (q == 2) ER_LOAD(3, 1);
; #pragma unroll
;             for (int mm = 0; mm < 2; ++mm) { const int ai = q >> 1, m = 2 * (q & 1) + mm; const size_t off = (size_t)(row0 + ai * HALF + m * 16) * ldc + col0; float ss = 0.f;
;                 const int rl = wr * 64 + fr + ai * HALF + m * 16, cl0 = col0; const size_t xoff = (size_t)u.pm * ((size_t)ldc * BM) + (size_t)rl * 64;
; #pragma unroll
;                 for (int bj = 0; bj < 2; ++bj)
; #pragma unroll
;                     for (int n = 0; n < 2; ++n) {
;                         const f32x4 o = pre[q & 1][mm][bj][n] + acc[ai][bj][m][n] * scale;
;                         *(f32x4*)(out + off + bj * HALF + n * 16) = o;
;                         if (COPY) { const f32x4 gn = *(const f32x4*)(gain + col0 + bj * HALF + n * 16); u32x2_ w; w.x = pk_bf16(o[0] * gn[0], o[1] * gn[1]); w.y = pk_bf16(o[2] * gn[2], o[3] * gn[3]); *(u32x2_*)(XB + xoff + (size_t)((cl0 + bj * HALF + n * 16) >> 6) * (256 * 64) + ((cl0 + bj * HALF + n * 16) & 63)) = w; ss += (o[0] * o[0] + o[1] * o[1]) + (o[2] * o[2] + o[3] * o[3]); } }
;                 if (COPY) { ss += __shfl_xor(ss, 16); ss += __shfl_xor(ss, 32); ssq[2 * q + mm] = ss; } }
;         }
	v_pk_mul_f32 v[140:141], v[32:33], v[220:221]
	v_pk_mul_f32 v[138:139], v[30:31], v[218:219]
	s_nop 0
	v_cvt_pk_bf16_f32 v138, v138, v139
	v_cvt_pk_bf16_f32 v139, v140, v141
	global_load_dwordx4 v[218:221], v[224:225], off offset:64
	global_store_dwordx2 v[150:151], v[138:139], off
	global_store_dwordx4 v[142:143], v[26:29], off offset:64
	s_waitcnt vmcnt(2)
	v_pk_mul_f32 v[140:141], v[28:29], v[220:221]
	v_pk_mul_f32 v[138:139], v[26:27], v[218:219]
	v_mul_f32_e32 v27, v27, v27
	v_cvt_pk_bf16_f32 v138, v138, v139
	v_cvt_pk_bf16_f32 v139, v140, v141
	global_load_dwordx4 v[218:221], v[224:225], off offset:512
	global_store_dwordx2 v[150:151], v[138:139], off offset:32
	global_store_dwordx4 v[142:143], v[22:25], off offset:512
	v_mul_f32_e32 v29, v29, v29
	v_fmac_f32_e32 v27, v26, v26
	v_fmac_f32_e32 v29, v28, v28
	s_waitcnt vmcnt(2)
	v_pk_mul_f32 v[140:141], v[24:25], v[220:221]
	v_pk_mul_f32 v[138:139], v[22:23], v[218:219]
	v_mul_f32_e32 v23, v23, v23
	v_cvt_pk_bf16_f32 v138, v138, v139
	v_cvt_pk_bf16_f32 v139, v140, v141
	global_load_dwordx4 v[218:221], v[224:225], off offset:576
	global_store_dwordx2 v[144:145], v[138:139], off
	global_store_dwordx4 v[142:143], v[18:21], off offset:576
	v_lshl_add_u64 v[138:139], s[48:49], 0, v[230:231]
	v_lshl_add_u64 v[138:139], v[138:139], 0, v[226:227]
	v_mul_f32_e32 v25, v25, v25
	v_fmac_f32_e32 v23, v22, v22
	v_fmac_f32_e32 v25, v24, v24
	s_waitcnt vmcnt(2)
	v_pk_mul_f32 v[142:143], v[20:21], v[220:221]
	v_pk_mul_f32 v[140:141], v[18:19], v[218:219]
	v_mul_f32_e32 v19, v19, v19
	v_cvt_pk_bf16_f32 v140, v140, v141
	v_cvt_pk_bf16_f32 v141, v142, v143
	global_load_dwordx4 v[218:221], v[224:225], off
	global_store_dwordx2 v[144:145], v[140:141], off offset:32
	global_store_dwordx4 v[138:139], v[14:17], off
	v_lshl_add_u64 v[144:145], s[34:35], 0, v[212:213]
	v_lshl_add_u64 v[150:151], v[144:145], 0, s[36:37]
	v_lshl_add_u64 v[150:151], v[150:151], 0, v[194:195]
	v_lshl_add_u64 v[144:145], v[144:145], 0, s[38:39]
	v_mul_f32_e32 v21, v21, v21
	v_fmac_f32_e32 v19, v18, v18
	v_fmac_f32_e32 v21, v20, v20
	s_waitcnt vmcnt(2)
	v_pk_mul_f32 v[142:143], v[16:17], v[220:221]
	v_pk_mul_f32 v[140:141], v[14:15], v[218:219]
	v_mul_f32_e32 v15, v15, v15
	v_cvt_pk_bf16_f32 v140, v140, v141
	v_cvt_pk_bf16_f32 v141, v142, v143
	global_load_dwordx4 v[218:221], v[224:225], off offset:64
	global_store_dwordx2 v[150:151], v[140:141], off
	global_store_dwordx4 v[138:139], v[10:13], off offset:64
	v_mul_f32_e32 v17, v17, v17
	v_fmac_f32_e32 v15, v14, v14
	v_fmac_f32_e32 v17, v16, v16
	v_add_f32_e32 v15, v15, v17
	v_add_f32_e32 v14, v19, v21
	s_waitcnt vmcnt(2)
	v_pk_mul_f32 v[6:7], v[12:13], v[220:221]
	v_pk_mul_f32 v[8:9], v[10:11], v[218:219]
	v_mov_b64_e32 v[218:219], 0x400
	v_mov_b64_e32 v[220:221], 0x3ff
	v_mul_f32_e32 v11, v11, v11
	v_cvt_pk_bf16_f32 v8, v8, v9
	v_cvt_pk_bf16_f32 v9, v6, v7
	global_store_dwordx2 v[150:151], v[8:9], off offset:32
	global_store_dwordx4 v[138:139], v[90:93], off offset:512
	global_load_dwordx4 v[94:97], v[224:225], off offset:512
	v_add_f32_e32 v6, v148, v149
	v_add_f32_e32 v7, v99, v101
	v_add_f32_e32 v6, v6, v7
	v_add_f32_e32 v7, v70, v72
	v_add_f32_e32 v70, v78, v80
	v_add_f32_e32 v72, v79, v75
	v_mul_f32_e32 v78, v51, v51
	v_mul_f32_e32 v79, v53, v53
	v_fmac_f32_e32 v78, v50, v50
	v_fmac_f32_e32 v79, v52, v52
	v_pk_fma_f32 v[52:53], v[4:5], 0.5, v[64:65] op_sel_hi:[1,0,1]
	v_pk_fma_f32 v[50:51], v[2:3], 0.5, v[62:63] op_sel_hi:[1,0,1]
	v_add_f32_e32 v7, v7, v74
	v_lshl_add_u64 v[74:75], v[144:145], 0, v[194:195]
	v_add_f32_e32 v7, v7, v76
	v_mul_f32_e32 v76, v55, v55
	v_fmac_f32_e32 v76, v54, v54
	v_mul_f32_e32 v13, v13, v13
	v_fmac_f32_e32 v11, v10, v10
	v_fmac_f32_e32 v13, v12, v12
	v_add_f32_e32 v10, v27, v29
	v_add_f32_e32 v11, v11, v13
	v_add_f32_e32 v8, v107, v109
	v_add_f32_e32 v12, v23, v25
	v_add_f32_e32 v9, v115, v117
	v_add_f32_e32 v6, v6, v8
	v_add_f32_e32 v8, v70, v82
	v_add_f32_e32 v70, v72, v71
	v_add_f32_e32 v6, v6, v9
	v_add_f32_e32 v8, v8, v83
	v_add_f32_e32 v70, v70, v73
	ds_bpermute_b32 v9, v146, v6
	ds_bpermute_b32 v71, v146, v7
	ds_bpermute_b32 v72, v146, v8
	ds_bpermute_b32 v73, v146, v70
	s_waitcnt lgkmcnt(3)
	v_add_f32_e32 v6, v6, v9
	s_waitcnt lgkmcnt(2)
	v_add_f32_e32 v7, v7, v71
	s_waitcnt lgkmcnt(1)
	v_add_f32_e32 v9, v8, v72
	s_waitcnt lgkmcnt(0)
	v_add_f32_e32 v71, v70, v73
	ds_bpermute_b32 v8, v147, v6
	ds_bpermute_b32 v70, v147, v7
	ds_bpermute_b32 v72, v147, v9
	ds_bpermute_b32 v73, v147, v71
	s_waitcnt vmcnt(0)
	v_pk_mul_f32 v[2:3], v[92:93], v[96:97]
	v_pk_mul_f32 v[4:5], v[90:91], v[94:95]
	s_nop 0
	v_cvt_pk_bf16_f32 v4, v4, v5
	v_cvt_pk_bf16_f32 v5, v2, v3
	global_store_dwordx2 v[74:75], v[4:5], off
	global_store_dwordx4 v[138:139], v[50:53], off offset:576
	global_load_dwordx4 v[54:57], v[224:225], off offset:576
	v_add_f32_e32 v2, v67, v69
	v_add_f32_e32 v3, v59, v61
	v_add_f32_e32 v4, v76, v77
	v_add_f32_e32 v2, v2, v3
	v_add_f32_e32 v5, v78, v79
	v_add_f32_e32 v2, v2, v4
	v_add_f32_e32 v2, v2, v5
	ds_bpermute_b32 v3, v146, v2
	v_add_f32_e32 v4, v34, v36
	v_add_f32_e32 v4, v4, v38
	v_mul_f32_e32 v34, v93, v93
	v_add_f32_e32 v4, v4, v35
	s_waitcnt lgkmcnt(0)
	v_add_f32_e32 v2, v2, v3
	v_mul_f32_e32 v3, v31, v31
	v_mul_f32_e32 v31, v33, v33
	v_mul_f32_e32 v33, v91, v91
	v_fmac_f32_e32 v3, v30, v30
	v_fmac_f32_e32 v31, v32, v32
	v_mul_f32_e32 v35, v51, v51
	v_mul_f32_e32 v36, v53, v53
	v_fmac_f32_e32 v33, v90, v90
	v_fmac_f32_e32 v34, v92, v92
	v_add_f32_e32 v3, v3, v31
	v_fmac_f32_e32 v35, v50, v50
	v_fmac_f32_e32 v36, v52, v52
	v_add_f32_e32 v13, v33, v34
	v_add_f32_e32 v3, v3, v10
	v_add_f32_e32 v10, v15, v11
	v_add_f32_e32 v16, v35, v36
	v_add_f32_e32 v3, v3, v12
	v_add_f32_e32 v10, v10, v13
	v_add_f32_e32 v3, v3, v14
	v_add_f32_e32 v12, v10, v16
	ds_bpermute_b32 v5, v146, v4
	ds_bpermute_b32 v14, v146, v3
	ds_bpermute_b32 v15, v146, v12
	ds_bpermute_b32 v10, v147, v2
	s_waitcnt lgkmcnt(3)
	v_add_f32_e32 v11, v4, v5
	s_waitcnt lgkmcnt(2)
	v_add_f32_e32 v3, v3, v14
	s_waitcnt lgkmcnt(1)
	v_add_f32_e32 v5, v12, v15
	ds_bpermute_b32 v13, v147, v11
	ds_bpermute_b32 v4, v147, v3
	ds_bpermute_b32 v12, v147, v5
	s_waitcnt vmcnt(0)
	v_pk_mul_f32 v[14:15], v[52:53], v[56:57]
	v_pk_mul_f32 v[16:17], v[50:51], v[54:55]
	s_nop 0
	v_cvt_pk_bf16_f32 v16, v16, v17
	v_cvt_pk_bf16_f32 v17, v14, v15
	global_store_dwordx2 v[74:75], v[16:17], off offset:32
	s_and_saveexec_b64 s[34:35], s[0:1]
	s_cbranch_execz .LBB0_279
;     __device__ __forceinline__ void operator()(const f32x4 (&acc)[2][2][4][2], const Unit& u, int wr, int wc, int fr, int fq) const {
;     ...
;                 if (COPY) { ss += __shfl_xor(ss, 16); ss += __shfl_xor(ss, 32); ssq[2 * q + mm] = ss; } }
;         }
;     ...
;         if (COPY) { if (fq == 0) {
; #pragma unroll
;             for (int i = 0; i < 8; ++i) atomicAdd(stat + row0 + (i >> 2) * HALF + (i & 3) * 16, ssq[i]); } }
	s_waitcnt lgkmcnt(3)
	v_add_f32_e32 v10, v2, v10
	v_add_f32_e32 v6, v6, v8
	s_waitcnt lgkmcnt(1)
	v_add_f32_e32 v4, v3, v4
	v_lshl_add_u64 v[2:3], v[222:223], 2, s[14:15]
	v_add_f32_e32 v11, v11, v13
	v_add_f32_e32 v13, v71, v73
	v_add_f32_e32 v9, v9, v72
	v_add_f32_e32 v7, v7, v70
	s_waitcnt lgkmcnt(0)
	v_add_f32_e32 v5, v5, v12
	global_atomic_add_f32 v[2:3], v6, off
	global_atomic_add_f32 v[2:3], v7, off offset:64
	global_atomic_add_f32 v[2:3], v9, off offset:128
	global_atomic_add_f32 v[2:3], v13, off offset:192
	global_atomic_add_f32 v[2:3], v10, off offset:512
	global_atomic_add_f32 v[2:3], v11, off offset:576
	global_atomic_add_f32 v[2:3], v4, off offset:640
	global_atomic_add_f32 v[2:3], v5, off offset:704
